# W1 / HG in-proj phase start: unit-table loads issued before the GEMM stage loads, table arithmetic and LDS writes after them (overlaps the two cold round trips)
# baseline (speedup 1.0000x reference)
.LBB0_226:
	s_lshr_b32 s66, s48, 1
	s_and_b32 s0, s48, 1
	s_cmp_eq_u32 s0, 0
	s_cselect_b64 s[12:13], -1, 0
	s_cmp_eq_u32 s0, 1
	v_writelane_b32 v244, s12, 55
	s_cselect_b64 s[0:1], -1, 0
	s_lshl_b32 s4, s48, 16
	v_writelane_b32 v244, s13, 56
	s_lshl_b64 s[12:13], s[4:5], 2
	v_readlane_b32 s4, v246, 60
	s_add_u32 s4, s4, s12
	s_nop 0
	v_writelane_b32 v244, s4, 57
	v_readlane_b32 s4, v246, 61
	s_addc_u32 s4, s4, s13
	s_and_b64 vcc, exec, s[0:1]
	v_writelane_b32 v244, s4, 58
	v_cmp_ne_u32_e64 s[0:1], 1, v198
	s_mov_b32 s4, s48
	s_nop 0
	v_writelane_b32 v244, s0, 59
	s_nop 1
	v_writelane_b32 v244, s1, 60
	s_mov_b64 s[0:1], -1
	v_writelane_b32 v244, s4, 61
	s_nop 1
	v_writelane_b32 v244, s5, 62
	s_cbranch_vccz .LBB0_809
	v_readlane_b32 s0, v244, 59
	v_readlane_b32 s1, v244, 60
	s_and_b64 vcc, exec, s[0:1]
	v_mbcnt_lo_u32_b32 v2, -1, 0
	v_mbcnt_hi_u32_b32 v2, -1, v2
	s_cbranch_vccnz .LBB0_258
	v_readlane_b32 s0, v246, 23
	s_nop 1
	v_add_u32_e32 v0, s0, v2
	s_movk_i32 s0, 0xff
	v_cmp_lt_i32_e64 s[14:15], s0, v0
	v_readlane_b32 s80, v244, 18
	v_readlane_b32 s81, v244, 19
	v_readlane_b32 s82, v244, 24
	v_readlane_b32 s83, v244, 25
	s_and_b64 s[80:81], s[80:81], s[82:83]
	s_andn2_b64 vcc, exec, s[80:81]
	s_cbranch_vccnz .Ltab2_hgin_orig
	v_readlane_b32 s86, v244, 16
	v_readlane_b32 s87, v244, 17
	s_nop 1
	v_cmp_gt_i64_e32 vcc, s[86:87], v[158:159]
	s_cbranch_vccz .Ltab2_hgin_orig
	v_readlane_b32 s88, v244, 57
	v_readlane_b32 s89, v244, 58
	s_mov_b64 s[90:91], s[14:15]
	v_lshl_add_u32 v229, v0, 2, 0
	s_and_saveexec_b64 s[84:85], s[14:15]
	s_xor_b64 s[84:85], exec, s[84:85]
	s_cbranch_execz .Ltab2_hgin_rows
	v_readlane_b32 s12, v245, 22
	v_readlane_b32 s13, v245, 23
	s_add_u32 s86, s88, s12
	s_addc_u32 s87, s89, s13
	v_readlane_b32 s12, v245, 20
	v_readlane_b32 s13, v245, 21
	s_lshl_b64 s[12:13], s[12:13], 2
	s_add_u32 s12, s86, s12
	s_addc_u32 s13, s87, s13
	v_lshl_add_u64 v[226:227], v[0:1], 2, s[12:13]
	global_load_dword v104, v[226:227], off offset:-1024
	v_readlane_b32 s12, v245, 57
	v_readlane_b32 s13, v245, 58
	s_add_u32 s86, s88, s12
	s_addc_u32 s87, s89, s13
	v_readlane_b32 s12, v245, 55
	v_readlane_b32 s13, v245, 56
	s_lshl_b64 s[12:13], s[12:13], 2
	s_add_u32 s12, s86, s12
	s_addc_u32 s13, s87, s13
	v_lshl_add_u64 v[226:227], v[0:1], 2, s[12:13]
	global_load_dword v120, v[226:227], off offset:-1024
	v_readlane_b32 s12, v245, 62
	v_readlane_b32 s13, v245, 63
	s_add_u32 s86, s88, s12
	s_addc_u32 s87, s89, s13
	v_readlane_b32 s12, v245, 60
	v_readlane_b32 s13, v245, 61
	s_lshl_b64 s[12:13], s[12:13], 2
	s_add_u32 s12, s86, s12
	s_addc_u32 s13, s87, s13
	v_lshl_add_u64 v[226:227], v[0:1], 2, s[12:13]
	global_load_dword v170, v[226:227], off offset:-1024
	v_readlane_b32 s12, v244, 3
	v_readlane_b32 s13, v244, 4
	s_add_u32 s86, s88, s12
	s_addc_u32 s87, s89, s13
	v_readlane_b32 s12, v244, 1
	v_readlane_b32 s13, v244, 2
	s_lshl_b64 s[12:13], s[12:13], 2
	s_add_u32 s12, s86, s12
	s_addc_u32 s13, s87, s13
	v_lshl_add_u64 v[226:227], v[0:1], 2, s[12:13]
	global_load_dword v210, v[226:227], off offset:-1024
.Ltab2_hgin_rows:
	s_andn2_saveexec_b64 s[84:85], s[84:85]
	s_cbranch_execz .Ltab2_hgin_join
	v_readlane_b32 s12, v245, 24
	s_nop 1
	v_add_u32_e32 v226, s12, v0
	v_ashrrev_i32_e32 v227, 31, v226
	v_lshlrev_b64 v[226:227], 6, v[226:227]
	v_lshl_add_u64 v[226:227], s[70:71], 0, v[226:227]
	global_load_dwordx4 v[104:107], v[226:227], off
	global_load_dwordx4 v[108:111], v[226:227], off offset:16
	global_load_dwordx4 v[112:115], v[226:227], off offset:32
	global_load_dwordx4 v[116:119], v[226:227], off offset:48
	v_readlane_b32 s12, v245, 59
	s_nop 1
	v_add_u32_e32 v226, s12, v0
	v_ashrrev_i32_e32 v227, 31, v226
	v_lshlrev_b64 v[226:227], 6, v[226:227]
	v_lshl_add_u64 v[226:227], s[70:71], 0, v[226:227]
	global_load_dwordx4 v[120:123], v[226:227], off
	global_load_dwordx4 v[124:127], v[226:227], off offset:16
	global_load_dwordx4 v[128:131], v[226:227], off offset:32
	global_load_dwordx4 v[132:135], v[226:227], off offset:48
	v_readlane_b32 s12, v244, 0
	s_nop 1
	v_add_u32_e32 v226, s12, v0
	v_ashrrev_i32_e32 v227, 31, v226
	v_lshlrev_b64 v[226:227], 6, v[226:227]
	v_lshl_add_u64 v[226:227], s[70:71], 0, v[226:227]
	global_load_dwordx4 v[170:173], v[226:227], off
	global_load_dwordx4 v[174:177], v[226:227], off offset:16
	global_load_dwordx4 v[178:181], v[226:227], off offset:32
	global_load_dwordx4 v[182:185], v[226:227], off offset:48
	v_readlane_b32 s12, v244, 5
	s_nop 1
	v_add_u32_e32 v226, s12, v0
	v_ashrrev_i32_e32 v227, 31, v226
	v_lshlrev_b64 v[226:227], 6, v[226:227]
	v_lshl_add_u64 v[226:227], s[70:71], 0, v[226:227]
	global_load_dwordx4 v[210:213], v[226:227], off
	global_load_dwordx4 v[214:217], v[226:227], off offset:16
	global_load_dwordx4 v[218:221], v[226:227], off offset:32
	global_load_dwordx4 v[222:225], v[226:227], off offset:48
.Ltab2_hgin_join:
	s_or_b64 exec, exec, s[84:85]
	v_readlane_b32 s0, v246, 23
	v_mbcnt_lo_u32_b32 v16, -1, 0
	v_mbcnt_hi_u32_b32 v16, -1, v16
	s_nop 0
	v_add_u32_e32 v0, s0, v16
	v_readlane_b32 s0, v244, 59
	v_readlane_b32 s1, v244, 60
	s_and_b64 vcc, exec, s[0:1]
	v_readfirstlane_b32 s14, v0
	s_cbranch_vccnz .LBB0_446
	v_lshlrev_b32_e32 v2, 4, v0
	v_add_u32_e32 v3, 0x2000, v2
	v_ashrrev_i32_e32 v4, 31, v3
	v_lshrrev_b32_e32 v4, 22, v4
	v_add_u32_e32 v4, v3, v4
	v_ashrrev_i32_e32 v10, 10, v4
	v_mul_i32_i24_e32 v4, 0x400, v10
	v_sub_u32_e32 v3, v3, v4
	v_lshrrev_b32_e32 v4, 4, v3
	v_bitop3_b32 v3, v4, v3, 32 bitop3:0x6c
	v_ashrrev_i32_e32 v4, 31, v3
	v_lshrrev_b32_e32 v4, 26, v4
	s_ashr_i32 s15, s14, 6
	v_add_u32_e32 v4, v3, v4
	v_lshlrev_b32_e32 v5, 3, v10
	s_ashr_i32 s20, s14, 8
	s_lshl_b32 s36, s15, 10
	s_lshl_b32 s0, s66, 23
	v_readlane_b32 s1, v246, 62
	v_ashrrev_i32_e32 v11, 6, v4
	v_and_b32_e32 v5, -16, v5
	s_add_u32 s37, s1, s0
	v_readlane_b32 s0, v246, 63
	v_add_u32_e32 v5, v11, v5
	s_addc_u32 s38, s0, 0
	v_and_b32_e32 v6, 3, v11
	s_mov_b32 s0, 0x1fffe0
	v_lshrrev_b32_e32 v7, 2, v5
	v_lshlrev_b32_e32 v8, 1, v5
	v_and_b32_e32 v4, 0xc0, v4
	v_and_or_b32 v6, v5, s0, v6
	v_and_b32_e32 v7, 4, v7
	v_and_b32_e32 v8, 24, v8
	v_sub_u32_e32 v3, v3, v4
	v_or3_b32 v6, v6, v7, v8
	v_lshlrev_b32_e32 v7, 5, v10
	v_ashrrev_i16_sdwa v3, v200, sext(v3) dst_sel:DWORD dst_unused:UNUSED_PAD src0_sel:DWORD src1_sel:BYTE_0
	v_and_b32_e32 v7, 32, v7
	v_bfe_i32 v12, v3, 0, 16
	v_add_lshl_u32 v3, v7, v12, 1
	v_lshl_add_u32 v146, v6, 11, v3
	v_lshl_add_u32 v148, v5, 11, v3
	v_bfe_i32 v3, v0, 27, 1
	v_lshrrev_b32_e32 v3, 22, v3
	v_add_u32_e32 v3, v2, v3
	v_and_b32_e32 v3, 0xfffffc00, v3
	v_sub_u32_e32 v2, v2, v3
	v_lshrrev_b32_e32 v3, 4, v2
	v_ashrrev_i32_e32 v4, 31, v0
	v_bitop3_b32 v2, v3, v2, 32 bitop3:0x6c
	v_lshrrev_b32_e32 v4, 26, v4
	v_ashrrev_i32_e32 v3, 31, v2
	v_add_u32_e32 v0, v0, v4
	v_lshrrev_b32_e32 v3, 26, v3
	v_ashrrev_i32_e32 v14, 6, v0
	v_add_u32_e32 v3, v2, v3
	v_lshlrev_b32_e32 v0, 3, v14
	v_ashrrev_i32_e32 v13, 6, v3
	v_and_b32_e32 v0, -16, v0
	v_add_u32_e32 v4, v13, v0
	v_and_b32_e32 v0, 3, v13
	v_and_or_b32 v0, v4, s0, v0
	v_readlane_b32 s0, v245, 35
	v_readlane_b32 s1, v245, 36
	s_mov_b32 s12, s0
	s_ashr_i32 s13, s0, 31
	v_writelane_b32 v245, s0, 35
	v_lshrrev_b32_e32 v5, 2, v4
	v_lshlrev_b32_e32 v6, 1, v4
	v_writelane_b32 v245, s1, 36
	s_lshl_b64 s[0:1], s[12:13], 19
	v_readlane_b32 s12, v245, 18
	v_and_b32_e32 v3, 0xc0, v3
	v_readlane_b32 s13, v245, 19
	v_and_b32_e32 v5, 4, v5
	v_and_b32_e32 v6, 24, v6
	v_sub_u32_e32 v2, v2, v3
	s_ashr_i32 s13, s12, 31
	v_or3_b32 v0, v0, v5, v6
	v_lshlrev_b32_e32 v5, 5, v14
	v_ashrrev_i16_sdwa v2, v200, sext(v2) dst_sel:DWORD dst_unused:UNUSED_PAD src0_sel:DWORD src1_sel:BYTE_0
	s_mov_b32 s4, s12
	s_lshl_b64 s[12:13], s[12:13], 19
	v_and_b32_e32 v5, 32, v5
	v_bfe_i32 v15, v2, 0, 16
	s_add_u32 s12, s37, s12
	v_add_lshl_u32 v2, v5, v15, 1
	s_addc_u32 s13, s38, s13
	s_add_i32 s39, s36, 0
	v_lshl_add_u32 v0, v0, 11, v2
	s_add_i32 m0, s39, 0x10000
	v_lshl_add_u32 v150, v4, 11, v2
	global_load_lds_dwordx4 v0, s[12:13]
	s_add_i32 m0, s39, 0x12000
	s_add_u32 s16, s12, 0x40000
	global_load_lds_dwordx4 v146, s[12:13]
	s_addc_u32 s17, s13, 0
	s_add_i32 m0, s39, 0x14000
	v_mov_b32_e32 v147, v1
	global_load_lds_dwordx4 v0, s[16:17]
	s_add_i32 m0, s39, 0x16000
	s_add_u32 s0, s96, s0
	s_addc_u32 s1, s97, s1
	s_add_i32 s40, s39, 0x2000
	global_load_lds_dwordx4 v146, s[16:17]
	s_mov_b32 m0, s39
	s_add_u32 s16, s0, 0x40000
	global_load_lds_dwordx4 v150, s[0:1]
	s_mov_b32 m0, s40
	s_addc_u32 s17, s1, 0
	s_add_i32 s41, s39, 0x4000
	global_load_lds_dwordx4 v148, s[0:1]
	s_mov_b32 m0, s41
	s_add_i32 s42, s39, 0x6000
	global_load_lds_dwordx4 v150, s[16:17]
	s_mov_b32 m0, s42
	v_mov_b32_e32 v151, v1
	global_load_lds_dwordx4 v148, s[16:17]
	v_mov_b32_e32 v149, v1
	s_cmp_eq_u32 s20, 1
	v_writelane_b32 v245, s4, 18
	v_lshl_add_u64 v[8:9], s[12:13], 0, v[0:1]
	v_lshl_add_u64 v[6:7], s[12:13], 0, v[146:147]
	v_lshl_add_u64 v[2:3], s[0:1], 0, v[150:151]
	s_cselect_b64 s[16:17], -1, 0
	s_waitcnt vmcnt(8)
	s_mov_b32 s93, 0x800000
	s_mov_b64 s[84:85], exec
	s_andn2_b64 exec, exec, s[90:91]
	s_cbranch_execz .Ltab2_hgin_wr
	v_pk_add_f32 v[106:107], v[106:107], v[110:111]
	v_pk_add_f32 v[104:105], v[104:105], v[108:109]
	v_pk_add_f32 v[108:109], v[114:115], v[118:119]
	v_pk_add_f32 v[110:111], v[112:113], v[116:117]
	v_pk_add_f32 v[106:107], v[106:107], v[108:109]
	v_pk_add_f32 v[104:105], v[104:105], v[110:111]
	s_nop 0
	v_pk_mov_b32 v[108:109], v[104:105], v[106:107] op_sel:[1,0]
	v_mov_b32_e32 v105, v107
	v_pk_add_f32 v[104:105], v[108:109], v[104:105]
	s_nop 0
	v_add_f32_e32 v228, v104, v105
	v_fmamk_f32 v228, v228, 0x3a800000, v199
	v_mul_f32_e32 v104, 0x4b800000, v228
	v_cmp_gt_f32_e32 vcc, s93, v228
	s_nop 1
	v_cndmask_b32_e32 v228, v228, v104, vcc
	v_rsq_f32_e32 v228, v228
	s_nop 0
	v_mul_f32_e32 v104, 0x45800000, v228
	v_cndmask_b32_e32 v104, v228, v104, vcc
	v_pk_add_f32 v[122:123], v[122:123], v[126:127]
	v_pk_add_f32 v[120:121], v[120:121], v[124:125]
	v_pk_add_f32 v[124:125], v[130:131], v[134:135]
	v_pk_add_f32 v[126:127], v[128:129], v[132:133]
	v_pk_add_f32 v[122:123], v[122:123], v[124:125]
	v_pk_add_f32 v[120:121], v[120:121], v[126:127]
	s_nop 0
	v_pk_mov_b32 v[124:125], v[120:121], v[122:123] op_sel:[1,0]
	v_mov_b32_e32 v121, v123
	v_pk_add_f32 v[120:121], v[124:125], v[120:121]
	s_nop 0
	v_add_f32_e32 v228, v120, v121
	v_fmamk_f32 v228, v228, 0x3a800000, v199
	v_mul_f32_e32 v120, 0x4b800000, v228
	v_cmp_gt_f32_e32 vcc, s93, v228
	s_nop 1
	v_cndmask_b32_e32 v228, v228, v120, vcc
	v_rsq_f32_e32 v228, v228
	s_nop 0
	v_mul_f32_e32 v120, 0x45800000, v228
	v_cndmask_b32_e32 v120, v228, v120, vcc
	v_pk_add_f32 v[172:173], v[172:173], v[176:177]
	v_pk_add_f32 v[170:171], v[170:171], v[174:175]
	v_pk_add_f32 v[174:175], v[180:181], v[184:185]
	v_pk_add_f32 v[176:177], v[178:179], v[182:183]
	v_pk_add_f32 v[172:173], v[172:173], v[174:175]
	v_pk_add_f32 v[170:171], v[170:171], v[176:177]
	s_nop 0
	v_pk_mov_b32 v[174:175], v[170:171], v[172:173] op_sel:[1,0]
	v_mov_b32_e32 v171, v173
	v_pk_add_f32 v[170:171], v[174:175], v[170:171]
	s_nop 0
	v_add_f32_e32 v228, v170, v171
	v_fmamk_f32 v228, v228, 0x3a800000, v199
	v_mul_f32_e32 v170, 0x4b800000, v228
	v_cmp_gt_f32_e32 vcc, s93, v228
	s_nop 1
	v_cndmask_b32_e32 v228, v228, v170, vcc
	v_rsq_f32_e32 v228, v228
	s_nop 0
	v_mul_f32_e32 v170, 0x45800000, v228
	v_cndmask_b32_e32 v170, v228, v170, vcc
	v_pk_add_f32 v[212:213], v[212:213], v[216:217]
	v_pk_add_f32 v[210:211], v[210:211], v[214:215]
	v_pk_add_f32 v[214:215], v[220:221], v[224:225]
	v_pk_add_f32 v[216:217], v[218:219], v[222:223]
	v_pk_add_f32 v[212:213], v[212:213], v[214:215]
	v_pk_add_f32 v[210:211], v[210:211], v[216:217]
	s_nop 0
	v_pk_mov_b32 v[214:215], v[210:211], v[212:213] op_sel:[1,0]
	v_mov_b32_e32 v211, v213
	v_pk_add_f32 v[210:211], v[214:215], v[210:211]
	s_nop 0
	v_add_f32_e32 v228, v210, v211
	v_fmamk_f32 v228, v228, 0x3a800000, v199
	v_mul_f32_e32 v210, 0x4b800000, v228
	v_cmp_gt_f32_e32 vcc, s93, v228
	s_nop 1
	v_cndmask_b32_e32 v228, v228, v210, vcc
	v_rsq_f32_e32 v228, v228
	s_nop 0
	v_mul_f32_e32 v210, 0x45800000, v228
	v_cndmask_b32_e32 v210, v228, v210, vcc
.Ltab2_hgin_wr:
	s_mov_b64 exec, s[84:85]
	v_add_u32_e32 v226, 0x20400, v229
	ds_write_b32 v226, v104
	v_add_u32_e32 v226, 0x20c00, v229
	ds_write_b32 v226, v120
	v_add_u32_e32 v226, 0x21400, v229
	ds_write_b32 v226, v170
	v_add_u32_e32 v226, 0x21c00, v229
	ds_write_b32 v226, v210
	s_branch .Ltab2_hgin_resume
.Ltab2_hgin_orig:
	s_and_saveexec_b64 s[0:1], s[14:15]
	s_xor_b64 s[0:1], exec, s[0:1]
	s_cbranch_execz .LBB0_230
	v_readlane_b32 s12, v245, 22
	v_readlane_b32 s4, v244, 57
	v_readlane_b32 s13, v245, 23
	s_add_u32 s4, s4, s12
	v_readlane_b32 s12, v244, 58
	s_addc_u32 s16, s12, s13
	v_readlane_b32 s12, v245, 20
	v_readlane_b32 s13, v245, 21
	s_lshl_b64 s[12:13], s[12:13], 2
	s_add_u32 s12, s4, s12
	s_addc_u32 s13, s16, s13
	v_lshl_add_u64 v[4:5], v[0:1], 2, s[12:13]
	global_load_dword v4, v[4:5], off offset:-1024

.Ltab2_hgin_resume:
	s_cmp_lg_u32 s20, 1
	v_lshl_add_u64 v[4:5], s[0:1], 0, v[148:149]
	v_writelane_b32 v245, s5, 19
	s_cbranch_scc1 .LBB0_261
	s_barrier

.LBB0_1347:
	v_readlane_b32 s0, v244, 59
	v_readlane_b32 s1, v244, 60
	s_and_b64 vcc, exec, s[0:1]
	s_waitcnt lgkmcnt(0)
	v_mbcnt_lo_u32_b32 v2, -1, 0
	v_mbcnt_hi_u32_b32 v2, -1, v2
	s_cbranch_vccnz .LBB0_1378
	v_readlane_b32 s0, v244, 57
	s_add_u32 s4, s0, 0x20000
	v_readlane_b32 s0, v244, 58
	s_addc_u32 s18, s0, 0
	v_readlane_b32 s0, v246, 23
	s_nop 1
	v_add_u32_e32 v0, s0, v2
	s_movk_i32 s0, 0xff
	v_cmp_lt_i32_e64 s[16:17], s0, v0
	v_readlane_b32 s80, v244, 18
	v_readlane_b32 s81, v244, 19
	v_readlane_b32 s82, v244, 24
	v_readlane_b32 s83, v244, 25
	s_and_b64 s[80:81], s[80:81], s[82:83]
	s_andn2_b64 vcc, exec, s[80:81]
	s_cbranch_vccnz .Ltab2_w1_orig
	v_readlane_b32 s86, v244, 16
	v_readlane_b32 s87, v244, 17
	s_nop 1
	v_cmp_gt_i64_e32 vcc, s[86:87], v[158:159]
	s_cbranch_vccz .Ltab2_w1_orig
	v_readlane_b32 s88, v244, 57
	v_readlane_b32 s89, v244, 58
	s_add_u32 s88, s88, 0x20000
	s_addc_u32 s89, s89, 0
	s_mov_b64 s[90:91], s[16:17]
	v_lshl_add_u32 v229, v0, 2, 0
	s_and_saveexec_b64 s[84:85], s[16:17]
	s_xor_b64 s[84:85], exec, s[84:85]
	s_cbranch_execz .Ltab2_w1_rows
	v_readlane_b32 s12, v245, 22
	v_readlane_b32 s13, v245, 23
	s_add_u32 s86, s88, s12
	s_addc_u32 s87, s89, s13
	v_readlane_b32 s12, v245, 20
	v_readlane_b32 s13, v245, 21
	s_lshl_b64 s[12:13], s[12:13], 2
	s_add_u32 s12, s86, s12
	s_addc_u32 s13, s87, s13
	v_lshl_add_u64 v[226:227], v[0:1], 2, s[12:13]
	global_load_dword v104, v[226:227], off offset:-1024
	v_readlane_b32 s12, v245, 57
	v_readlane_b32 s13, v245, 58
	s_add_u32 s86, s88, s12
	s_addc_u32 s87, s89, s13
	v_readlane_b32 s12, v245, 55
	v_readlane_b32 s13, v245, 56
	s_lshl_b64 s[12:13], s[12:13], 2
	s_add_u32 s12, s86, s12
	s_addc_u32 s13, s87, s13
	v_lshl_add_u64 v[226:227], v[0:1], 2, s[12:13]
	global_load_dword v120, v[226:227], off offset:-1024
	v_readlane_b32 s12, v245, 62
	v_readlane_b32 s13, v245, 63
	s_add_u32 s86, s88, s12
	s_addc_u32 s87, s89, s13
	v_readlane_b32 s12, v245, 60
	v_readlane_b32 s13, v245, 61
	s_lshl_b64 s[12:13], s[12:13], 2
	s_add_u32 s12, s86, s12
	s_addc_u32 s13, s87, s13
	v_lshl_add_u64 v[226:227], v[0:1], 2, s[12:13]
	global_load_dword v170, v[226:227], off offset:-1024
	v_readlane_b32 s12, v244, 3
	v_readlane_b32 s13, v244, 4
	s_add_u32 s86, s88, s12
	s_addc_u32 s87, s89, s13
	v_readlane_b32 s12, v244, 1
	v_readlane_b32 s13, v244, 2
	s_lshl_b64 s[12:13], s[12:13], 2
	s_add_u32 s12, s86, s12
	s_addc_u32 s13, s87, s13
	v_lshl_add_u64 v[226:227], v[0:1], 2, s[12:13]
	global_load_dword v210, v[226:227], off offset:-1024

.Ltab2_w1_join:
	s_or_b64 exec, exec, s[84:85]
	v_readlane_b32 s0, v246, 23
	v_mbcnt_lo_u32_b32 v8, -1, 0
	v_mbcnt_hi_u32_b32 v8, -1, v8
	s_lshl_b64 s[44:45], s[76:77], 23
	v_add_u32_e32 v0, s0, v8
	v_readlane_b32 s0, v244, 59
	v_readlane_b32 s1, v244, 60
	s_and_b64 vcc, exec, s[0:1]
	v_readfirstlane_b32 s12, v0
	s_cbranch_vccnz .LBB0_1398
	v_lshlrev_b32_e32 v5, 4, v0
	v_add_u32_e32 v3, 0x2000, v5
	v_ashrrev_i32_e32 v2, 31, v3
	v_lshrrev_b32_e32 v2, 22, v2
	v_add_u32_e32 v2, v3, v2
	v_ashrrev_i32_e32 v2, 10, v2
	v_mul_i32_i24_e32 v4, 0x400, v2
	v_sub_u32_e32 v3, v3, v4
	v_lshrrev_b32_e32 v4, 4, v3
	v_bitop3_b32 v4, v4, v3, 32 bitop3:0x6c
	v_ashrrev_i32_e32 v3, 31, v4
	v_lshrrev_b32_e32 v3, 26, v3
	s_ashr_i32 s13, s12, 6
	v_add_u32_e32 v6, v4, v3
	v_lshlrev_b32_e32 v7, 3, v2
	s_ashr_i32 s16, s12, 8
	s_lshl_b32 s4, s13, 10
	v_readlane_b32 s0, v245, 14
	v_ashrrev_i32_e32 v3, 6, v6
	v_and_b32_e32 v7, -16, v7
	s_add_u32 s34, s0, s44
	v_readlane_b32 s0, v245, 15
	v_add_u32_e32 v7, v3, v7
	s_addc_u32 s35, s0, s45
	v_and_b32_e32 v9, 3, v3
	s_mov_b32 s0, 0x1fffe0
	v_lshrrev_b32_e32 v10, 2, v7
	v_lshlrev_b32_e32 v11, 1, v7
	v_and_b32_e32 v6, 0xc0, v6
	v_and_or_b32 v9, v7, s0, v9
	v_and_b32_e32 v10, 4, v10
	v_and_b32_e32 v11, 24, v11
	v_sub_u32_e32 v4, v4, v6
	v_or3_b32 v9, v9, v10, v11
	v_lshlrev_b32_e32 v10, 5, v2
	v_ashrrev_i16_sdwa v4, v200, sext(v4) dst_sel:DWORD dst_unused:UNUSED_PAD src0_sel:DWORD src1_sel:BYTE_0
	v_and_b32_e32 v10, 32, v10
	v_bfe_i32 v4, v4, 0, 16
	v_add_lshl_u32 v6, v10, v4, 1
	v_lshl_add_u32 v146, v9, 11, v6
	v_lshl_add_u32 v148, v7, 11, v6
	v_bfe_i32 v6, v0, 27, 1
	v_lshrrev_b32_e32 v6, 22, v6
	v_add_u32_e32 v6, v5, v6
	v_and_b32_e32 v6, 0xfffffc00, v6
	v_sub_u32_e32 v5, v5, v6
	v_lshrrev_b32_e32 v6, 4, v5
	v_bitop3_b32 v7, v6, v5, 32 bitop3:0x6c
	v_ashrrev_i32_e32 v6, 31, v0
	v_lshrrev_b32_e32 v6, 26, v6
	v_ashrrev_i32_e32 v5, 31, v7
	v_add_u32_e32 v0, v0, v6
	v_lshrrev_b32_e32 v5, 26, v5
	v_ashrrev_i32_e32 v6, 6, v0
	v_add_u32_e32 v9, v7, v5
	v_lshlrev_b32_e32 v0, 3, v6
	v_ashrrev_i32_e32 v5, 6, v9
	v_and_b32_e32 v0, -16, v0
	v_add_u32_e32 v10, v5, v0
	v_and_b32_e32 v0, 3, v5
	v_lshrrev_b32_e32 v11, 2, v10
	v_lshlrev_b32_e32 v12, 1, v10
	v_and_b32_e32 v9, 0xc0, v9
	v_and_or_b32 v0, v10, s0, v0
	v_and_b32_e32 v11, 4, v11
	v_and_b32_e32 v12, 24, v12
	v_sub_u32_e32 v7, v7, v9
	v_or3_b32 v0, v0, v11, v12
	v_lshlrev_b32_e32 v11, 5, v6
	v_ashrrev_i16_sdwa v7, v200, sext(v7) dst_sel:DWORD dst_unused:UNUSED_PAD src0_sel:DWORD src1_sel:BYTE_0
	v_readlane_b32 s0, v245, 32
	v_and_b32_e32 v11, 32, v11
	v_bfe_i32 v7, v7, 0, 16
	v_readlane_b32 s1, v245, 33
	s_add_u32 s28, s34, s0
	v_add_lshl_u32 v9, v11, v7, 1
	s_addc_u32 s29, s35, s1
	s_add_i32 s36, s4, 0
	v_lshl_add_u32 v0, v0, 11, v9
	s_add_i32 m0, s36, 0x10000
	v_lshl_add_u32 v150, v10, 11, v9
	global_load_lds_dwordx4 v0, s[28:29]
	s_add_i32 m0, s36, 0x12000
	s_add_u32 s0, s28, 0x40000
	global_load_lds_dwordx4 v146, s[28:29]
	s_addc_u32 s1, s29, 0
	s_add_i32 m0, s36, 0x14000
	s_add_i32 s37, s36, 0x2000
	global_load_lds_dwordx4 v0, s[0:1]
	s_add_i32 m0, s36, 0x16000
	s_add_i32 s38, s36, 0x4000
	global_load_lds_dwordx4 v146, s[0:1]
	v_readlane_b32 s0, v245, 37
	s_mov_b32 m0, s36
	v_readlane_b32 s1, v245, 38
	s_add_i32 s39, s36, 0x6000
	s_cmp_eq_u32 s16, 1
	s_nop 2
	global_load_lds_dwordx4 v150, s[0:1]
	s_mov_b32 m0, s37
	s_nop 0
	global_load_lds_dwordx4 v148, s[0:1]
	v_readlane_b32 s0, v245, 39
	s_mov_b32 m0, s38
	v_readlane_b32 s1, v245, 40
	s_nop 4
	global_load_lds_dwordx4 v150, s[0:1]
	s_mov_b32 m0, s39
	s_nop 0
	global_load_lds_dwordx4 v148, s[0:1]
	s_cselect_b64 s[0:1], -1, 0
	s_waitcnt vmcnt(8)
	s_mov_b32 s93, 0x800000
	s_mov_b64 s[84:85], exec
	s_andn2_b64 exec, exec, s[90:91]
	s_cbranch_execz .Ltab2_w1_wr
	v_pk_add_f32 v[106:107], v[106:107], v[110:111]
	v_pk_add_f32 v[104:105], v[104:105], v[108:109]
	v_pk_add_f32 v[108:109], v[114:115], v[118:119]
	v_pk_add_f32 v[110:111], v[112:113], v[116:117]
	v_pk_add_f32 v[106:107], v[106:107], v[108:109]
	v_pk_add_f32 v[104:105], v[104:105], v[110:111]
	s_nop 0
	v_pk_mov_b32 v[108:109], v[104:105], v[106:107] op_sel:[1,0]
	v_mov_b32_e32 v105, v107
	v_pk_add_f32 v[104:105], v[108:109], v[104:105]
	s_nop 0
	v_add_f32_e32 v228, v104, v105
	v_fmamk_f32 v228, v228, 0x3a800000, v199
	v_mul_f32_e32 v104, 0x4b800000, v228
	v_cmp_gt_f32_e32 vcc, s93, v228
	s_nop 1
	v_cndmask_b32_e32 v228, v228, v104, vcc
	v_rsq_f32_e32 v228, v228
	s_nop 0
	v_mul_f32_e32 v104, 0x45800000, v228
	v_cndmask_b32_e32 v104, v228, v104, vcc
	v_pk_add_f32 v[122:123], v[122:123], v[126:127]
	v_pk_add_f32 v[120:121], v[120:121], v[124:125]
	v_pk_add_f32 v[124:125], v[130:131], v[134:135]
	v_pk_add_f32 v[126:127], v[128:129], v[132:133]
	v_pk_add_f32 v[122:123], v[122:123], v[124:125]
	v_pk_add_f32 v[120:121], v[120:121], v[126:127]
	s_nop 0
	v_pk_mov_b32 v[124:125], v[120:121], v[122:123] op_sel:[1,0]
	v_mov_b32_e32 v121, v123
	v_pk_add_f32 v[120:121], v[124:125], v[120:121]
	s_nop 0
	v_add_f32_e32 v228, v120, v121
	v_fmamk_f32 v228, v228, 0x3a800000, v199
	v_mul_f32_e32 v120, 0x4b800000, v228
	v_cmp_gt_f32_e32 vcc, s93, v228
	s_nop 1
	v_cndmask_b32_e32 v228, v228, v120, vcc
	v_rsq_f32_e32 v228, v228
	s_nop 0
	v_mul_f32_e32 v120, 0x45800000, v228
	v_cndmask_b32_e32 v120, v228, v120, vcc
	v_pk_add_f32 v[172:173], v[172:173], v[176:177]
	v_pk_add_f32 v[170:171], v[170:171], v[174:175]
	v_pk_add_f32 v[174:175], v[180:181], v[184:185]
	v_pk_add_f32 v[176:177], v[178:179], v[182:183]
	v_pk_add_f32 v[172:173], v[172:173], v[174:175]
	v_pk_add_f32 v[170:171], v[170:171], v[176:177]
	s_nop 0
	v_pk_mov_b32 v[174:175], v[170:171], v[172:173] op_sel:[1,0]
	v_mov_b32_e32 v171, v173
	v_pk_add_f32 v[170:171], v[174:175], v[170:171]
	s_nop 0
	v_add_f32_e32 v228, v170, v171
	v_fmamk_f32 v228, v228, 0x3a800000, v199
	v_mul_f32_e32 v170, 0x4b800000, v228
	v_cmp_gt_f32_e32 vcc, s93, v228
	s_nop 1
	v_cndmask_b32_e32 v228, v228, v170, vcc
	v_rsq_f32_e32 v228, v228
	s_nop 0
	v_mul_f32_e32 v170, 0x45800000, v228
	v_cndmask_b32_e32 v170, v228, v170, vcc
	v_pk_add_f32 v[212:213], v[212:213], v[216:217]
	v_pk_add_f32 v[210:211], v[210:211], v[214:215]
	v_pk_add_f32 v[214:215], v[220:221], v[224:225]
	v_pk_add_f32 v[216:217], v[218:219], v[222:223]
	v_pk_add_f32 v[212:213], v[212:213], v[214:215]
	v_pk_add_f32 v[210:211], v[210:211], v[216:217]
	s_nop 0
	v_pk_mov_b32 v[214:215], v[210:211], v[212:213] op_sel:[1,0]
	v_mov_b32_e32 v211, v213
	v_pk_add_f32 v[210:211], v[214:215], v[210:211]
	s_nop 0
	v_add_f32_e32 v228, v210, v211
	v_fmamk_f32 v228, v228, 0x3a800000, v199
	v_mul_f32_e32 v210, 0x4b800000, v228
	v_cmp_gt_f32_e32 vcc, s93, v228
	s_nop 1
	v_cndmask_b32_e32 v228, v228, v210, vcc
	v_rsq_f32_e32 v228, v228
	s_nop 0
	v_mul_f32_e32 v210, 0x45800000, v228
	v_cndmask_b32_e32 v210, v228, v210, vcc

.Ltab2_w1_orig:
	s_and_saveexec_b64 s[0:1], s[16:17]
	s_xor_b64 s[0:1], exec, s[0:1]
	s_cbranch_execz .LBB0_1350
	v_readlane_b32 s12, v245, 22
	v_readlane_b32 s13, v245, 23
	s_add_u32 s19, s4, s12
	s_addc_u32 s20, s18, s13
	v_readlane_b32 s12, v245, 20
	v_readlane_b32 s13, v245, 21
	s_lshl_b64 s[12:13], s[12:13], 2
	s_add_u32 s12, s19, s12
	s_addc_u32 s13, s20, s13
	v_lshl_add_u64 v[4:5], v[0:1], 2, s[12:13]
	global_load_dword v4, v[4:5], off offset:-1024

.Ltab2_w1_resume:
	s_cmp_lg_u32 s16, 1
	s_cbranch_scc1 .LBB0_1381
	s_barrier
